# v29 + attention work queue split into 8 per-XCD queues (physical XCC id, with stealing): the 16 query tiles of one (batch, head) are consecutive entries so co-resident workgroups stream the same K/V t
# baseline (speedup 1.0000x reference)
; DI int TIDX() { int t = (int)threadIdx.x; asm volatile("" : "+v"(t)); return t; }
; DI void phase_d(const Params& p, int layer, unsigned char* smem) {
;   unsigned* qctr = (unsigned*)(p.ws + O_BAR) + 130 + layer;
;   int* s_it = (int*)(smem + SMEM_BYTES - 16);
;   for (;;) {
;     if (TIDX() == 0) *s_it = (int)atomicAdd(qctr, 1u);
;     __syncthreads();
;     const int it = *s_it;
;     __syncthreads();
;     if (it >= PD_ITEMS) break;
.LBB0_585:
	s_or_b64 exec, exec, s[0:1]
	v_readlane_b32 s0, v241, 0
	v_readlane_b32 s1, v241, 1
	s_add_u32 s2, s0, 0x9554000
	s_addc_u32 s3, s1, 0
	v_writelane_b32 v237, s2, 13
	v_mbcnt_hi_u32_b32 v221, -1, v184
	s_movk_i32 s70, 0xff80
	v_writelane_b32 v237, s3, 14
	s_add_u32 s2, s0, 0x4b54000
	s_addc_u32 s3, s1, 0
	v_writelane_b32 v240, s2, 26
	s_waitcnt lgkmcnt(0)
	v_and_b32_e32 v0, 64, v221
	s_mov_b32 s69, 0
	v_writelane_b32 v240, s3, 27
	s_add_u32 s2, s0, 0x1df54000
	s_addc_u32 s3, s1, 0
	v_writelane_b32 v240, s2, 35
	v_mov_b32_e32 v1, 0
	v_mov_b32_e32 v174, 0x23ff0
	v_writelane_b32 v240, s3, 36
	s_add_u32 s2, s0, 0xcd54000
	v_writelane_b32 v237, s2, 15
	s_addc_u32 s2, s1, 0
	v_writelane_b32 v237, s2, 16
	s_add_u32 s2, s0, 0xdd54000
	v_writelane_b32 v237, s2, 17
	s_addc_u32 s2, s1, 0
	v_writelane_b32 v237, s2, 18
	s_add_u32 s2, s0, 0x1e554000
	v_writelane_b32 v240, s2, 28
	s_addc_u32 s2, s1, 0
	v_writelane_b32 v240, s2, 29
	s_add_u32 s2, s0, 0xc554000
	v_writelane_b32 v237, s2, 19
	s_addc_u32 s2, s1, 0
	v_writelane_b32 v237, s2, 20
	s_add_u32 s2, s0, 0xd554000
	v_writelane_b32 v237, s2, 21
	s_addc_u32 s2, s1, 0
	v_writelane_b32 v237, s2, 22
	s_add_u32 s2, s0, 0x1b754000
	s_addc_u32 s3, s1, 0
	v_writelane_b32 v240, s2, 23
	s_mov_b32 s84, 0x2aaaaaab
	s_movk_i32 s85, 0x200
	v_writelane_b32 v240, s3, 24
	s_add_u32 s2, s0, 0xe554000
	s_addc_u32 s3, s1, 0
	v_writelane_b32 v240, s2, 30
	s_movk_i32 s86, 0x48
	s_movk_i32 s87, 0x220
	v_writelane_b32 v240, s3, 31
	s_add_u32 s2, s0, 0x10554000
	s_addc_u32 s3, s1, 0
	v_writelane_b32 v237, s2, 23
	s_mov_b32 s88, 0x41800000
	s_movk_i32 s90, 0x600
	v_writelane_b32 v237, s3, 24
	s_add_u32 s2, s0, 0x1e354000
	v_writelane_b32 v237, s2, 25
	s_addc_u32 s2, s1, 0
	v_writelane_b32 v237, s2, 26
	s_add_u32 s2, s0, 0x12554000
	v_writelane_b32 v237, s2, 27
	s_addc_u32 s2, s1, 0
	v_writelane_b32 v237, s2, 28
	s_add_u32 s2, s0, 0x14554000
	s_addc_u32 s3, s1, 0
	v_writelane_b32 v240, s2, 14
	s_mov_b32 s71, -1
	s_movk_i32 s92, 0x68
	v_writelane_b32 v240, s3, 15
	s_add_u32 s2, s0, 0x17554000
	s_addc_u32 s3, s1, 0
	v_writelane_b32 v237, s2, 29
	v_xor_b32_e32 v222, 32, v221
	v_add_u32_e32 v223, 64, v0
	v_writelane_b32 v237, s3, 30
	s_add_u32 s2, s0, 0x1b554000
	s_addc_u32 s3, s1, 0
	s_add_u32 s0, s0, 0x19554000
	s_addc_u32 s1, s1, 0
	v_writelane_b32 v240, s2, 32
	v_writelane_b32 v237, s0, 31
	v_mov_b32_e32 v175, 0xff800000
	s_barrier
	v_writelane_b32 v240, s3, 33
	v_writelane_b32 v237, s1, 32
	s_getreg_b32 s98, hwreg(HW_REG_XCC_ID, 0, 4)
	s_and_b32 s98, s98, 7
	s_mov_b32 s99, 0
	s_branch .LBB0_590

; DI int TIDX() { int t = (int)threadIdx.x; asm volatile("" : "+v"(t)); return t; }
; DI void phase_d(const Params& p, int layer, unsigned char* smem) {
;     ...
;   for (;;) {
;     if (TIDX() == 0) *s_it = (int)atomicAdd(qctr, 1u);
;     __syncthreads();
;     const int it = *s_it;
.LBB0_590:
	v_mov_b32_e32 v0, v220
	s_nop 0
	v_cmp_eq_u32_e32 vcc, 0, v0
	s_and_saveexec_b64 s[0:1], vcc
	s_cbranch_execz .LBB0_594
	s_mov_b64 s[4:5], exec
	v_mbcnt_lo_u32_b32 v0, s4, 0
	v_mbcnt_hi_u32_b32 v0, s5, v0
	v_cmp_eq_u32_e32 vcc, 0, v0
	s_and_saveexec_b64 s[2:3], vcc
	s_cbranch_execz .LBB0_593
	s_bcnt1_i32_b64 s4, s[4:5]
	v_mov_b32_e32 v2, s4
	v_readlane_b32 s4, v241, 0
	v_readlane_b32 s5, v241, 1
	s_nop 4
	s_lshl_b32 s100, s98, 2
	s_add_u32 s4, s4, s100
	s_addc_u32 s5, s5, 0
	global_atomic_add v2, v1, v2, s[4:5] offset:528 sc0

; DI int TIDX() { int t = (int)threadIdx.x; asm volatile("" : "+v"(t)); return t; }
; DI void phase_d(const Params& p, int layer, unsigned char* smem) {
;     ...
;     if (TIDX() == 0) *s_it = (int)atomicAdd(qctr, 1u);
;     __syncthreads();
;     const int it = *s_it;
;     __syncthreads();
;     if (it >= PD_ITEMS) break;
;     const int r = it / 192, w = it % 192, qt = 15 - r;
.LBB0_594:
	s_or_b64 exec, exec, s[0:1]
	s_waitcnt lgkmcnt(0)
	s_barrier
	ds_read_b32 v0, v174
	s_movk_i32 s0, 0xbff
	s_waitcnt lgkmcnt(0)
	s_barrier
	v_readfirstlane_b32 s2, v0
	s_nop 3
	s_cmp_lt_u32 s2, 0x180
	s_cbranch_scc1 .Lxq0_ok
	s_add_i32 s99, s99, 1
	s_add_i32 s98, s98, 1
	s_and_b32 s98, s98, 7
	s_cmp_lt_u32 s99, 8
	s_cbranch_scc1 .LBB0_590
	s_mov_b64 s[0:1], -1
	s_branch .LBB0_589
.Lxq0_ok:
	s_lshr_b32 s100, s2, 4
	s_and_b32 s2, s2, 15
	s_mul_i32 s2, s2, 0xc0
	s_cmp_lt_u32 s100, 16
	s_cbranch_scc0 .Lxq0_nsa
	s_lshl_b32 s100, s100, 3
	s_add_i32 s100, s100, s98
	s_branch .Lxq0_w
.Lxq0_nsa:
	s_sub_i32 s100, s100, 16
	s_and_b32 s101, s100, 1
	s_lshl_b32 s101, s101, 3
	s_add_i32 s101, s101, s98
	s_lshr_b32 s100, s100, 1
	s_lshl_b32 s100, s100, 4
	s_add_i32 s100, s100, s101
	s_add_i32 s100, s100, 0x80
; DI void nsa_attn_item(const Params& p, int b, int g, int qt, bf16_t* smem) {
;   const int lane = TIDX() & 63, wid = TIDX() >> 6, l31 = lane & 31, half = lane >> 5;
;   const int t0 = qt * 64, tw0 = t0 + (wid >> 2) * 32, tq = tw0 + l31, head = g * 4 + (wid & 3); const size_t trow = (size_t)b * S_ + tq;
;   bf16x8 qf[4];
;   const bf16_t* qp = (const bf16_t*)(p.ws + O_NSAQ) + trow * 512 + head * 64;
; #pragma unroll
;   for (int ks = 0; ks < 4; ++ks) qf[ks] = *(const bf16x8*)(qp + ks * 16 + half * 8);
;   {
;     const float* rp = (const float*)(p.ws + O_ROPE8) + trow * 16;
;     u32x4 me = __builtin_bit_cast(u32x4, qf[0]), ot;
; #pragma unroll
;     for (int e = 0; e < 4; ++e) ot[e] = __shfl_xor(me[e], 32);
;     unsigned res[4];
; #pragma unroll
;     for (int e = 0; e < 4; ++e) {
;       float o2[2];
; #pragma unroll
;       for (int u = 0; u < 2; ++u) {
;         const int f = 2 * e + u; const float cs = rp[2 * f], sn = rp[2 * f + 1];
;         const float a = bf2f((bf16_t)(u ? me[e] >> 16 : me[e] & 0xffffu)), o = bf2f((bf16_t)(u ? ot[e] >> 16 : ot[e] & 0xffffu));
;         o2[u] = half == 0 ? a * cs - o * sn : a * cs + o * sn;
;       }
;       res[e] = pk2(o2[0], o2[1]);
;     }
;     qf[0] = __builtin_bit_cast(bf16x8, (u32x4){res[0], res[1], res[2], res[3]});
;   }
;   const float* gts = (const float*)(p.ws + O_GATES) + trow * 24 + head * 3;
;   const int cur = t0 >> 6;
;   f32x16 res[2];
;   {
;     AState st; astate_init(st);
;     const int first = t0 >= 511 ? (t0 - 511) >> 6 : 0, firstw = tw0 >= 511 ? (tw0 - 511) >> 6 : 0;
;     const u64 tmask = lowbits(cur + 1) & ~lowbits(first), wmask = lowbits(cur + 1) & ~lowbits(firstw);
;     flash_pass<M_WIN>(st, qf, tmask, wmask, (const bf16_t*)(p.ws + O_KWIN) + (size_t)b * S_ * 128 + g * 64, 128, nullptr,
;                       (const bf16_t*)(p.ws + O_VWINT) + (size_t)(b * 2 + g) * 64 * S_, nullptr, tq, 0ull, smem);
; DI void phase_d(const Params& p, int layer, unsigned char* smem) {
;     ...
;     const int r = it / 192, w = it % 192, qt = 15 - r;
;     if (w < 64) dense_attn_item<M_MLA>(p, w >> 3, w & 7, qt, (bf16_t*)smem);
;     else if (w < 128) dense_attn_item<M_FOX>(p, (w - 64) >> 3, (w - 64) & 7, qt, (bf16_t*)smem);
;     else { const int i = w - 128, bg = i & 15, q4 = i >> 4; nsa_attn_item(p, bg >> 1, bg & 1, qt * 4 + q4, (bf16_t*)smem); }
.Lxq0_w:
	s_add_i32 s2, s2, s100
	s_mov_b64 s[0:1], -1
	s_mul_hi_i32 s0, s2, 0xd5555555
	s_lshr_b32 s1, s0, 31
	s_ashr_i32 s73, s0, 5
	s_mul_hi_i32 s0, s2, 0x2aaaaaab
	s_add_i32 s73, s73, s1
	s_lshr_b32 s1, s0, 31
	s_lshr_b32 s0, s0, 5
	s_add_i32 s0, s0, s1
	s_mulk_i32 s0, 0xc0
	s_sub_i32 s72, s2, s0
	s_add_i32 s93, s73, 15
	s_cmp_gt_i32 s72, 63
	s_mov_b64 s[0:1], -1
	s_cbranch_scc0 .LBB0_706
	s_cmpk_gt_u32 s72, 0x7f
	s_cbranch_scc0 .LBB0_664
	s_add_i32 s0, s72, 0xffffff80
	v_mov_b32_e32 v17, v220
	v_mov_b32_e32 v0, v220
	s_lshr_b32 s0, s0, 4
	s_lshl_b32 s1, s93, 2
	s_add_i32 s0, s1, s0
	v_lshrrev_b32_e32 v10, 6, v0
	v_ashrrev_i32_e32 v0, 3, v0
	s_lshl_b32 s16, s0, 6
	v_and_b32_e32 v0, 0xffffffe0, v0
	v_add_u32_e32 v16, s16, v0
	v_and_or_b32 v160, v17, 31, v16
	s_lshl_b32 s1, s72, 11
	s_and_b32 s68, s1, 0x7000
	v_ashrrev_i32_e32 v161, 31, v160
	s_waitcnt vmcnt(9)
	v_lshl_add_u64 v[112:113], v[160:161], 0, s[68:69]
	v_readlane_b32 s4, v240, 26
	s_and_b32 s2, s72, 1
	v_lshlrev_b64 v[2:3], 6, v[112:113]
	v_readlane_b32 s5, v240, 27
	s_lshl_b32 s1, s2, 2
	v_and_or_b32 v122, v10, 3, s1
	v_lshl_add_u64 v[14:15], s[4:5], 0, v[2:3]
	v_readlane_b32 s4, v237, 13
	v_lshlrev_b64 v[22:23], 10, v[112:113]
	v_readlane_b32 s5, v237, 14
	global_load_dwordx4 v[2:5], v[14:15], off offset:16
	global_load_dwordx4 v[6:9], v[14:15], off
	v_bfe_u32 v177, v17, 5, 1
	global_load_dwordx4 v[10:13], v[14:15], off offset:48
	global_load_dwordx4 v[18:21], v[14:15], off offset:32
	v_lshl_add_u64 v[14:15], s[4:5], 0, v[22:23]
	v_lshlrev_b32_e32 v0, 7, v122
	v_lshl_add_u64 v[14:15], v[14:15], 0, v[0:1]
	v_lshlrev_b32_e32 v0, 4, v177
	v_lshl_add_u64 v[14:15], v[14:15], 0, v[0:1]
	global_load_dwordx4 v[22:25], v[14:15], off
	global_load_dwordx4 v[128:131], v[14:15], off offset:32
	global_load_dwordx4 v[132:135], v[14:15], off offset:64
	global_load_dwordx4 v[136:139], v[14:15], off offset:96
	v_cmp_lt_i32_e32 vcc, v222, v223
	v_and_b32_e32 v123, 63, v17
	s_add_i32 s1, s16, 0xfffffe01
	v_cndmask_b32_e32 v0, v221, v222, vcc
	v_lshlrev_b32_e32 v176, 2, v0
	s_ashr_i32 s1, s1, 6
	s_cmp_gt_u32 s0, 7
	s_cselect_b32 s3, s1, 0
	s_add_i32 s1, s0, 1
	s_lshl_b64 s[4:5], -1, s1
	s_not_b64 s[4:5], s[4:5]
	v_cmp_gt_u32_e32 vcc, 32, v123
	s_cmp_lt_u32 s0, 63
	s_cselect_b32 s7, s5, -1
	s_cselect_b32 s6, s4, -1
	s_lshl_b64 s[0:1], -1, s3
	s_cmp_lt_i32 s3, 64
	s_cselect_b32 s1, s1, 0
	s_cselect_b32 s0, s0, 0
	s_and_b32 s20, s72, 15
	s_and_b64 s[0:1], s[0:1], s[6:7]
	s_lshl_b32 s19, s68, 7
	s_lshl_b32 s18, s2, 6
	s_lshl_b32 s17, s20, 18
	s_cmp_eq_u64 s[0:1], 0
	s_waitcnt vmcnt(6)
	v_mov_b32_e32 v15, v8
	v_mov_b32_e32 v8, v7
	v_mov_b32_e32 v7, v4
	v_mov_b32_e32 v4, v3
	s_waitcnt vmcnt(4)
	v_mov_b32_e32 v3, v20
	v_mov_b32_e32 v20, v19
	v_mov_b32_e32 v19, v12
	v_mov_b32_e32 v12, v11
	s_waitcnt vmcnt(3)
	ds_bpermute_b32 v17, v176, v23
	ds_bpermute_b32 v34, v176, v25
	ds_bpermute_b32 v0, v176, v22
	ds_bpermute_b32 v32, v176, v24
	v_mov_b32_e32 v14, v6
	s_waitcnt lgkmcnt(3)
	v_and_b32_e32 v31, 0xffff0000, v17
	v_lshlrev_b32_e32 v30, 16, v17
	s_waitcnt lgkmcnt(2)
	v_and_b32_e32 v35, 0xffff0000, v34
	v_lshlrev_b32_e32 v34, 16, v34
	v_pk_mul_f32 v[4:5], v[4:5], v[30:31]
	v_pk_mul_f32 v[12:13], v[12:13], v[34:35]
	v_mov_b32_e32 v6, v2
	v_mov_b32_e32 v2, v18
	v_mov_b32_e32 v18, v10
	v_lshlrev_b32_e32 v10, 16, v22
	v_and_b32_e32 v11, 0xffff0000, v22
	v_lshlrev_b32_e32 v22, 16, v23
	v_and_b32_e32 v23, 0xffff0000, v23
	v_lshlrev_b32_e32 v26, 16, v24
	v_and_b32_e32 v27, 0xffff0000, v24
	v_lshlrev_b32_e32 v24, 16, v25
	v_and_b32_e32 v25, 0xffff0000, v25
	s_waitcnt lgkmcnt(1)
	v_and_b32_e32 v29, 0xffff0000, v0
	v_lshlrev_b32_e32 v28, 16, v0
	s_waitcnt lgkmcnt(0)
	v_and_b32_e32 v33, 0xffff0000, v32
	v_lshlrev_b32_e32 v32, 16, v32
	v_cndmask_b32_e64 v5, v5, -v5, vcc
	v_cndmask_b32_e64 v4, v4, -v4, vcc
	v_cndmask_b32_e64 v13, v13, -v13, vcc
	v_cndmask_b32_e64 v12, v12, -v12, vcc
	v_pk_mul_f32 v[8:9], v[8:9], v[28:29]
	v_pk_mul_f32 v[20:21], v[20:21], v[32:33]
	v_pk_fma_f32 v[4:5], v[6:7], v[22:23], v[4:5]
	v_pk_fma_f32 v[6:7], v[18:19], v[24:25], v[12:13]
	v_mov_b32_e32 v18, v220
	v_cndmask_b32_e64 v9, v9, -v9, vcc
	v_cndmask_b32_e64 v8, v8, -v8, vcc
	v_cndmask_b32_e64 v21, v21, -v21, vcc
	v_cndmask_b32_e64 v20, v20, -v20, vcc
	v_pk_fma_f32 v[8:9], v[14:15], v[10:11], v[8:9]
	v_and_b32_e32 v17, 31, v18
	v_pk_fma_f32 v[2:3], v[2:3], v[26:27], v[20:21]
	v_sub_u32_e32 v0, v160, v17
	v_cvt_pk_bf16_f32 v140, v8, v9
	v_cvt_pk_bf16_f32 v141, v4, v5
	v_cvt_pk_bf16_f32 v142, v2, v3
	v_cvt_pk_bf16_f32 v143, v6, v7
	v_readfirstlane_b32 s21, v0
	s_cbranch_scc1 .LBB0_625
	s_lshl_b32 s2, s19, 1
	v_readlane_b32 s3, v237, 15
	s_add_u32 s2, s3, s2
	v_readlane_b32 s3, v237, 16
	s_addc_u32 s3, s3, 0
	s_lshl_b32 s4, s18, 1
	s_add_u32 s2, s2, s4
	s_addc_u32 s3, s3, 0
	s_lshl_b32 s4, s17, 1
	v_readlane_b32 s5, v237, 17
	s_add_u32 s10, s5, s4
	v_readlane_b32 s4, v237, 18
	s_addc_u32 s11, s4, 0
	s_add_u32 s4, s0, -1
	s_addc_u32 s5, s1, -1
	s_ff1_i32_b64 s15, s[0:1]
	s_and_b64 s[4:5], s[4:5], s[0:1]
	s_lshl_b32 s68, s15, 7
	s_cmp_eq_u64 s[4:5], 0
	s_cselect_b64 s[8:9], -1, 0
	s_ff1_i32_b64 s12, s[4:5]
	v_min_i32_e32 v0, 0x1ff, v18
	v_ashrrev_i32_e32 v22, 3, v18
	s_and_b64 s[0:1], s[8:9], exec
	v_ashrrev_i32_e32 v124, 3, v0
	v_ashrrev_i32_e32 v23, 31, v22
	s_cselect_b32 s0, s15, s12
	v_lshlrev_b64 v[2:3], 13, v[22:23]
	v_lshlrev_b32_e32 v19, 3, v18
	v_lshl_add_u32 v4, s0, 6, v124
	v_lshlrev_b32_e32 v0, 3, v0
	v_lshl_add_u64 v[14:15], s[10:11], 0, v[2:3]
	v_and_b32_e32 v20, 56, v19
	v_ashrrev_i32_e32 v5, 31, v4
	v_and_b32_e32 v0, 56, v0
	v_lshl_add_u64 v[2:3], v[14:15], 0, s[68:69]
	v_lshlrev_b32_e32 v114, 1, v20
	v_mov_b32_e32 v115, v1
	v_lshlrev_b64 v[4:5], 8, v[4:5]
	v_lshl_add_u64 v[2:3], v[2:3], 0, v[114:115]
	v_lshl_add_u64 v[4:5], s[2:3], 0, v[4:5]
	v_lshlrev_b32_e32 v0, 1, v0
	s_lshl_b32 s68, s0, 7
	v_lshl_add_u64 v[4:5], v[4:5], 0, v[0:1]
	global_load_dwordx4 v[10:13], v[2:3], off
	global_load_dwordx4 v[6:9], v[4:5], off
	v_lshl_add_u64 v[2:3], v[14:15], 0, s[68:69]
	v_lshl_add_u64 v[2:3], v[2:3], 0, v[114:115]
	global_load_dwordx4 v[2:5], v[2:3], off
	v_cmp_gt_i32_e64 s[0:1], s85, v18
	v_mul_lo_u32 v125, v22, s86
	s_and_saveexec_b64 s[10:11], s[0:1]
	s_cbranch_execz .LBB0_600
	s_lshl_b32 s13, s15, 6
	v_add_u32_e32 v22, s13, v124
	v_ashrrev_i32_e32 v23, 31, v22
	v_lshlrev_b64 v[22:23], 8, v[22:23]
	v_lshl_add_u64 v[22:23], s[2:3], 0, v[22:23]
	v_lshl_add_u64 v[22:23], v[22:23], 0, v[0:1]
	global_load_dwordx4 v[22:25], v[22:23], off
	v_lshl_add_u32 v21, v125, 1, v114
	s_waitcnt vmcnt(0)
	ds_write_b128 v21, v[22:25]

; DI int TIDX() { int t = (int)threadIdx.x; asm volatile("" : "+v"(t)); return t; }
; DI void phase_d(const Params& p, int layer, unsigned char* smem) {
;   unsigned* qctr = (unsigned*)(p.ws + O_BAR) + 130 + layer;
;   int* s_it = (int*)(smem + SMEM_BYTES - 16);
;   for (;;) {
;     if (TIDX() == 0) *s_it = (int)atomicAdd(qctr, 1u);
;     __syncthreads();
;     const int it = *s_it;
;     __syncthreads();
.LBB0_1619:
	s_or_b64 exec, exec, s[0:1]
	s_movk_i32 s70, 0xff80
	s_mov_b32 s69, 0
	v_mov_b32_e32 v1, 0
	v_mov_b32_e32 v174, 0x23ff0
	s_mov_b32 s84, 0x2aaaaaab
	s_movk_i32 s85, 0x200
	s_movk_i32 s86, 0x48
	s_movk_i32 s87, 0x220
	s_mov_b32 s88, 0x41800000
	s_movk_i32 s90, 0x600
	s_mov_b32 s71, -1
	s_movk_i32 s92, 0x68
	v_mov_b32_e32 v175, 0xff800000
	s_waitcnt lgkmcnt(0)
	s_barrier
	s_getreg_b32 s98, hwreg(HW_REG_XCC_ID, 0, 4)
	s_and_b32 s98, s98, 7
	s_mov_b32 s99, 0
	s_branch .LBB0_1624

; DI int TIDX() { int t = (int)threadIdx.x; asm volatile("" : "+v"(t)); return t; }
; DI void phase_d(const Params& p, int layer, unsigned char* smem) {
;     ...
;   for (;;) {
;     if (TIDX() == 0) *s_it = (int)atomicAdd(qctr, 1u);
;     __syncthreads();
;     const int it = *s_it;
.LBB0_1624:
	v_mov_b32_e32 v0, v220
	s_nop 0
	v_cmp_eq_u32_e32 vcc, 0, v0
	s_and_saveexec_b64 s[0:1], vcc
	s_cbranch_execz .LBB0_1628
	s_mov_b64 s[4:5], exec
	v_mbcnt_lo_u32_b32 v0, s4, 0
	v_mbcnt_hi_u32_b32 v0, s5, v0
	v_cmp_eq_u32_e32 vcc, 0, v0
	s_and_saveexec_b64 s[2:3], vcc
	s_cbranch_execz .LBB0_1627
	s_bcnt1_i32_b64 s4, s[4:5]
	v_mov_b32_e32 v2, s4
	v_readlane_b32 s4, v241, 0
	v_readlane_b32 s5, v241, 1
	s_nop 4
	s_lshl_b32 s100, s98, 2
	s_add_u32 s4, s4, s100
	s_addc_u32 s5, s5, 0
	global_atomic_add v2, v1, v2, s[4:5] offset:560 sc0

; template <int MODE>
; DI void flash_pass(AState& st, const bf16x8* qf, u64 tmask, u64 wmask,
;                    const bf16_t* kbase, size_t kld, const bf16_t* kpe, const bf16_t* vtbase, const float* fbias,
;                    int tq, u64 mysel, bf16_t* smem) {
;     ...
;   auto gload = [&](int j, auto setc) {
;     constexpr int S = decltype(setc)::value;
;     const int k0 = j * 64;
; #pragma unroll
;     for (int i = 0; i < C::KCH; ++i) {
; DI void nsa_attn_item(const Params& p, int b, int g, int qt, bf16_t* smem) {
;   const int lane = TIDX() & 63, wid = TIDX() >> 6, l31 = lane & 31, half = lane >> 5;
;   const int t0 = qt * 64, tw0 = t0 + (wid >> 2) * 32, tq = tw0 + l31, head = g * 4 + (wid & 3); const size_t trow = (size_t)b * S_ + tq;
;   bf16x8 qf[4];
;   const bf16_t* qp = (const bf16_t*)(p.ws + O_NSAQ) + trow * 512 + head * 64;
; #pragma unroll
;   for (int ks = 0; ks < 4; ++ks) qf[ks] = *(const bf16x8*)(qp + ks * 16 + half * 8);
;   {
;     const float* rp = (const float*)(p.ws + O_ROPE8) + trow * 16;
;     u32x4 me = __builtin_bit_cast(u32x4, qf[0]), ot;
; #pragma unroll
;     for (int e = 0; e < 4; ++e) ot[e] = __shfl_xor(me[e], 32);
;     unsigned res[4];
; #pragma unroll
;     for (int e = 0; e < 4; ++e) {
;       float o2[2];
; #pragma unroll
;       for (int u = 0; u < 2; ++u) {
;         const int f = 2 * e + u; const float cs = rp[2 * f], sn = rp[2 * f + 1];
;         const float a = bf2f((bf16_t)(u ? me[e] >> 16 : me[e] & 0xffffu)), o = bf2f((bf16_t)(u ? ot[e] >> 16 : ot[e] & 0xffffu));
;         o2[u] = half == 0 ? a * cs - o * sn : a * cs + o * sn;
;       }
;       res[e] = pk2(o2[0], o2[1]);
;     }
;     qf[0] = __builtin_bit_cast(bf16x8, (u32x4){res[0], res[1], res[2], res[3]});
;   }
;   const float* gts = (const float*)(p.ws + O_GATES) + trow * 24 + head * 3;
;   const int cur = t0 >> 6;
;   f32x16 res[2];
;   {
;     AState st; astate_init(st);
;     const int first = t0 >= 511 ? (t0 - 511) >> 6 : 0, firstw = tw0 >= 511 ? (tw0 - 511) >> 6 : 0;
;     const u64 tmask = lowbits(cur + 1) & ~lowbits(first), wmask = lowbits(cur + 1) & ~lowbits(firstw);
;     flash_pass<M_WIN>(st, qf, tmask, wmask, (const bf16_t*)(p.ws + O_KWIN) + (size_t)b * S_ * 128 + g * 64, 128, nullptr,
;                       (const bf16_t*)(p.ws + O_VWINT) + (size_t)(b * 2 + g) * 64 * S_, nullptr, tq, 0ull, smem);
.Lxq1_w:
	s_add_i32 s2, s2, s100
	s_mov_b64 s[0:1], -1
	s_mul_hi_i32 s0, s2, 0xd5555555
	s_lshr_b32 s1, s0, 31
	s_ashr_i32 s73, s0, 5
	s_mul_hi_i32 s0, s2, 0x2aaaaaab
	s_add_i32 s73, s73, s1
	s_lshr_b32 s1, s0, 31
	s_lshr_b32 s0, s0, 5
	s_add_i32 s0, s0, s1
	s_mulk_i32 s0, 0xc0
	s_sub_i32 s72, s2, s0
	s_add_i32 s93, s73, 15
	s_cmp_gt_i32 s72, 63
	s_mov_b64 s[0:1], -1
	s_cbranch_scc0 .LBB0_1740
	s_cmpk_gt_u32 s72, 0x7f
	s_cbranch_scc0 .LBB0_1698
	s_add_i32 s0, s72, 0xffffff80
	s_waitcnt vmcnt(9)
	v_mov_b32_e32 v17, v220
	v_mov_b32_e32 v0, v220
	s_lshr_b32 s0, s0, 4
	s_lshl_b32 s1, s93, 2
	s_add_i32 s0, s1, s0
	v_lshrrev_b32_e32 v10, 6, v0
	v_ashrrev_i32_e32 v0, 3, v0
	s_lshl_b32 s16, s0, 6
	v_and_b32_e32 v0, 0xffffffe0, v0
	v_add_u32_e32 v16, s16, v0
	v_and_or_b32 v160, v17, 31, v16
	s_lshl_b32 s1, s72, 11
	s_and_b32 s68, s1, 0x7000
	v_ashrrev_i32_e32 v161, 31, v160
	v_lshl_add_u64 v[112:113], v[160:161], 0, s[68:69]
	v_readlane_b32 s4, v240, 26
	s_and_b32 s2, s72, 1
	v_lshlrev_b64 v[2:3], 6, v[112:113]
	v_readlane_b32 s5, v240, 27
	s_lshl_b32 s1, s2, 2
	v_and_or_b32 v122, v10, 3, s1
	v_lshl_add_u64 v[14:15], s[4:5], 0, v[2:3]
	v_readlane_b32 s4, v237, 13
	s_waitcnt vmcnt(8)
	v_lshlrev_b64 v[22:23], 10, v[112:113]
	v_readlane_b32 s5, v237, 14
	global_load_dwordx4 v[2:5], v[14:15], off offset:16
	global_load_dwordx4 v[6:9], v[14:15], off
	v_bfe_u32 v177, v17, 5, 1
	global_load_dwordx4 v[10:13], v[14:15], off offset:48
	global_load_dwordx4 v[18:21], v[14:15], off offset:32
	v_lshl_add_u64 v[14:15], s[4:5], 0, v[22:23]
	v_lshlrev_b32_e32 v0, 7, v122
	v_lshl_add_u64 v[14:15], v[14:15], 0, v[0:1]
	v_lshlrev_b32_e32 v0, 4, v177
	v_lshl_add_u64 v[14:15], v[14:15], 0, v[0:1]
	global_load_dwordx4 v[22:25], v[14:15], off
	global_load_dwordx4 v[128:131], v[14:15], off offset:32
	global_load_dwordx4 v[132:135], v[14:15], off offset:64
	global_load_dwordx4 v[136:139], v[14:15], off offset:96
	v_cmp_lt_i32_e32 vcc, v222, v223
	v_and_b32_e32 v123, 63, v17
	s_add_i32 s1, s16, 0xfffffe01
	v_cndmask_b32_e32 v0, v221, v222, vcc
	v_lshlrev_b32_e32 v176, 2, v0
	s_ashr_i32 s1, s1, 6
	s_cmp_gt_u32 s0, 7
	s_cselect_b32 s3, s1, 0
	s_add_i32 s1, s0, 1
	s_lshl_b64 s[4:5], -1, s1
	s_not_b64 s[4:5], s[4:5]
	v_cmp_gt_u32_e32 vcc, 32, v123
	s_cmp_lt_u32 s0, 63
	s_cselect_b32 s7, s5, -1
	s_cselect_b32 s6, s4, -1
	s_lshl_b64 s[0:1], -1, s3
	s_cmp_lt_i32 s3, 64
	s_cselect_b32 s1, s1, 0
	s_cselect_b32 s0, s0, 0
	s_and_b32 s20, s72, 15
	s_and_b64 s[0:1], s[0:1], s[6:7]
	s_lshl_b32 s19, s68, 7
	s_lshl_b32 s18, s2, 6
	s_lshl_b32 s17, s20, 18
	s_cmp_eq_u64 s[0:1], 0
	s_waitcnt vmcnt(6)
	v_mov_b32_e32 v15, v8
	v_mov_b32_e32 v8, v7
	v_mov_b32_e32 v7, v4
	v_mov_b32_e32 v4, v3
	s_waitcnt vmcnt(4)
	v_mov_b32_e32 v3, v20
	v_mov_b32_e32 v20, v19
	v_mov_b32_e32 v19, v12
	v_mov_b32_e32 v12, v11
	s_waitcnt vmcnt(3)
	ds_bpermute_b32 v17, v176, v23
	ds_bpermute_b32 v34, v176, v25
	ds_bpermute_b32 v0, v176, v22
	ds_bpermute_b32 v32, v176, v24
	v_mov_b32_e32 v14, v6
	s_waitcnt lgkmcnt(3)
	v_and_b32_e32 v31, 0xffff0000, v17
	v_lshlrev_b32_e32 v30, 16, v17
	s_waitcnt lgkmcnt(2)
	v_and_b32_e32 v35, 0xffff0000, v34
	v_lshlrev_b32_e32 v34, 16, v34
	v_pk_mul_f32 v[4:5], v[4:5], v[30:31]
	v_pk_mul_f32 v[12:13], v[12:13], v[34:35]
	v_mov_b32_e32 v6, v2
	v_mov_b32_e32 v2, v18
	v_mov_b32_e32 v18, v10
	v_lshlrev_b32_e32 v10, 16, v22
	v_and_b32_e32 v11, 0xffff0000, v22
	v_lshlrev_b32_e32 v22, 16, v23
	v_and_b32_e32 v23, 0xffff0000, v23
	v_lshlrev_b32_e32 v26, 16, v24
	v_and_b32_e32 v27, 0xffff0000, v24
	v_lshlrev_b32_e32 v24, 16, v25
	v_and_b32_e32 v25, 0xffff0000, v25
	s_waitcnt lgkmcnt(1)
	v_and_b32_e32 v29, 0xffff0000, v0
	v_lshlrev_b32_e32 v28, 16, v0
	s_waitcnt lgkmcnt(0)
	v_and_b32_e32 v33, 0xffff0000, v32
	v_lshlrev_b32_e32 v32, 16, v32
	v_cndmask_b32_e64 v5, v5, -v5, vcc
	v_cndmask_b32_e64 v4, v4, -v4, vcc
	v_cndmask_b32_e64 v13, v13, -v13, vcc
	v_cndmask_b32_e64 v12, v12, -v12, vcc
	v_pk_mul_f32 v[8:9], v[8:9], v[28:29]
	v_pk_mul_f32 v[20:21], v[20:21], v[32:33]
	v_pk_fma_f32 v[4:5], v[6:7], v[22:23], v[4:5]
	v_pk_fma_f32 v[6:7], v[18:19], v[24:25], v[12:13]
	v_mov_b32_e32 v18, v220
	v_cndmask_b32_e64 v9, v9, -v9, vcc
	v_cndmask_b32_e64 v8, v8, -v8, vcc
	v_cndmask_b32_e64 v21, v21, -v21, vcc
	v_cndmask_b32_e64 v20, v20, -v20, vcc
	v_pk_fma_f32 v[8:9], v[14:15], v[10:11], v[8:9]
	v_and_b32_e32 v17, 31, v18
	v_pk_fma_f32 v[2:3], v[2:3], v[26:27], v[20:21]
	v_sub_u32_e32 v0, v160, v17
	v_cvt_pk_bf16_f32 v140, v8, v9
	v_cvt_pk_bf16_f32 v141, v4, v5
	v_cvt_pk_bf16_f32 v142, v2, v3
	v_cvt_pk_bf16_f32 v143, v6, v7
	v_readfirstlane_b32 s21, v0
	s_cbranch_scc1 .LBB0_1659
	s_lshl_b32 s2, s19, 1
	v_readlane_b32 s3, v237, 15
	s_add_u32 s2, s3, s2
	v_readlane_b32 s3, v237, 16
	s_addc_u32 s3, s3, 0
	s_lshl_b32 s4, s18, 1
	s_add_u32 s2, s2, s4
	s_addc_u32 s3, s3, 0
	s_lshl_b32 s4, s17, 1
	v_readlane_b32 s5, v237, 17
	s_add_u32 s10, s5, s4
	v_readlane_b32 s4, v237, 18
	s_addc_u32 s11, s4, 0
	s_add_u32 s4, s0, -1
	s_addc_u32 s5, s1, -1
	s_ff1_i32_b64 s15, s[0:1]
	s_and_b64 s[4:5], s[4:5], s[0:1]
	s_lshl_b32 s68, s15, 7
	s_cmp_eq_u64 s[4:5], 0
	s_cselect_b64 s[8:9], -1, 0
	s_ff1_i32_b64 s12, s[4:5]
	v_min_i32_e32 v0, 0x1ff, v18
	v_ashrrev_i32_e32 v22, 3, v18
	s_and_b64 s[0:1], s[8:9], exec
	v_ashrrev_i32_e32 v124, 3, v0
	v_ashrrev_i32_e32 v23, 31, v22
	s_cselect_b32 s0, s15, s12
	v_lshlrev_b64 v[2:3], 13, v[22:23]
	v_lshlrev_b32_e32 v19, 3, v18
	v_lshl_add_u32 v4, s0, 6, v124
	v_lshlrev_b32_e32 v0, 3, v0
	v_lshl_add_u64 v[14:15], s[10:11], 0, v[2:3]
	v_and_b32_e32 v20, 56, v19
	v_ashrrev_i32_e32 v5, 31, v4
	v_and_b32_e32 v0, 56, v0
	v_lshl_add_u64 v[2:3], v[14:15], 0, s[68:69]
	v_lshlrev_b32_e32 v114, 1, v20
	v_mov_b32_e32 v115, v1
	v_lshlrev_b64 v[4:5], 8, v[4:5]
	v_lshl_add_u64 v[2:3], v[2:3], 0, v[114:115]
	v_lshl_add_u64 v[4:5], s[2:3], 0, v[4:5]
	v_lshlrev_b32_e32 v0, 1, v0
	s_lshl_b32 s68, s0, 7
	v_lshl_add_u64 v[4:5], v[4:5], 0, v[0:1]
	global_load_dwordx4 v[10:13], v[2:3], off
	global_load_dwordx4 v[6:9], v[4:5], off
	v_lshl_add_u64 v[2:3], v[14:15], 0, s[68:69]
	v_lshl_add_u64 v[2:3], v[2:3], 0, v[114:115]
	global_load_dwordx4 v[2:5], v[2:3], off
	v_cmp_gt_i32_e64 s[0:1], s85, v18
	v_mul_lo_u32 v125, v22, s86
	s_and_saveexec_b64 s[10:11], s[0:1]
	s_cbranch_execz .LBB0_1634
	s_lshl_b32 s13, s15, 6
	v_add_u32_e32 v22, s13, v124
	v_ashrrev_i32_e32 v23, 31, v22
	v_lshlrev_b64 v[22:23], 8, v[22:23]
	v_lshl_add_u64 v[22:23], s[2:3], 0, v[22:23]
	v_lshl_add_u64 v[22:23], v[22:23], 0, v[0:1]
	global_load_dwordx4 v[22:25], v[22:23], off
	v_lshl_add_u32 v21, v125, 1, v114
	s_waitcnt vmcnt(0)
	ds_write_b128 v21, v[22:25]
